# stick-breaking chain block: v_mov-packed v_pk_mul_f32 pairs replaced by plain v_mul_f32 (30 fewer VALU per key tile)
# speedup vs baseline: 1.0064x; 1.0044x over previous
.LBB0_703:
	v_mul_f32_e32 v204, v33, v32
	v_mul_f32_e32 v205, v34, v35
	v_mul_f32_e32 v206, v37, v36
	v_mul_f32_e32 v207, v38, v39
	v_mul_f32_e32 v208, v181, v180
	v_mul_f32_e32 v209, v184, v185
	v_pk_mul_f32 v[216:217], v[208:209], v[208:209] op_sel:[0,1] op_sel_hi:[1,0]
	v_mul_f32_e32 v208, v41, v40
	v_mul_f32_e32 v209, v42, v43
	v_mul_f32_e32 v218, v189, v188
	v_mul_f32_e32 v219, v192, v193
	v_mov_b32_e32 v230, v44
	v_and_b32_e32 v44, 64, v226
	v_mul_f32_e32 v32, v218, v219
	v_xor_b32_e32 v40, 32, v226
	v_add_u32_e32 v44, 64, v44
	v_mul_f32_e32 v218, v45, v230
	v_mul_f32_e32 v219, v46, v47
	v_cmp_lt_i32_e32 vcc, v40, v44
	v_mul_f32_e32 v230, v199, v198
	v_mul_f32_e32 v231, v200, v201
	s_movk_i32 s8, 0xe000
	v_cndmask_b32_e32 v40, v226, v40, vcc
	v_mul_f32_e32 v36, v230, v231
	v_lshlrev_b32_e32 v64, 2, v40
	ds_bpermute_b32 v44, v64, v36
	ds_bpermute_b32 v40, v64, v32
	ds_bpermute_b32 v217, v64, v216
	s_add_i32 s74, s74, -1
	s_add_i32 s4, s4, -1
	s_waitcnt lgkmcnt(2)
	v_cndmask_b32_e64 v167, 1.0, v44, s[42:43]
	v_mul_f32_e32 v231, v159, v167
	v_mul_f32_e32 v230, v201, v231
	v_mul_f32_e32 v201, v200, v230
	v_mul_f32_e32 v200, v199, v201
	v_mul_f32_e32 v36, v36, v44
	v_pk_mul_f32 v[198:199], v[202:203], v[200:201]
	v_mul_f32_e32 v201, v159, v36
	s_waitcnt lgkmcnt(1)
	v_cndmask_b32_e64 v36, 1.0, v40, s[42:43]
	v_mul_f32_e32 v203, v36, v201
	v_mul_f32_e32 v202, v193, v203
	v_mul_f32_e32 v193, v192, v202
	v_mul_f32_e32 v192, v189, v193
	v_pk_mul_f32 v[188:189], v[190:191], v[192:193]
	v_mul_f32_e32 v191, v32, v40
	v_mul_f32_e32 v190, v176, v177
	v_mul_f32_e32 v191, v191, v201
	s_waitcnt lgkmcnt(0)
	v_mul_f32_e32 v192, v172, v173
	v_mul_f32_e32 v193, v216, v217
	v_cndmask_b32_e64 v32, 1.0, v217, s[42:43]
	v_pk_mul_f32 v[192:193], v[192:193], v[190:191]
	ds_bpermute_b32 v201, v64, v192
	v_mul_f32_e32 v191, v32, v191
	v_mul_f32_e32 v190, v185, v191
	v_mul_f32_e32 v185, v184, v190
	v_mul_f32_e32 v184, v181, v185
	s_waitcnt lgkmcnt(0)
	v_cndmask_b32_e64 v32, 1.0, v201, s[42:43]
	v_pk_mul_f32 v[180:181], v[182:183], v[184:185]
	v_mul_f32_e32 v183, v32, v193
	v_mul_f32_e32 v182, v177, v183
	v_mul_f32_e32 v177, v176, v182
	v_mul_f32_e32 v176, v173, v177
	v_pk_mul_f32 v[172:173], v[174:175], v[176:177]
	v_mul_f32_e32 v174, v218, v219
	v_mul_f32_e32 v175, v192, v201
	ds_bpermute_b32 v192, v64, v174
	v_pk_mul_f32 v[186:187], v[186:187], v[190:191]
	v_pk_mul_f32 v[178:179], v[178:179], v[182:183]
	v_pk_mul_f32 v[196:197], v[196:197], v[230:231]
	v_pk_mul_f32 v[194:195], v[194:195], v[202:203]
	s_waitcnt lgkmcnt(0)
	v_cndmask_b32_e64 v32, 1.0, v192, s[42:43]
	v_pk_mul_f32 v[174:175], v[174:175], v[192:193]
	s_mov_b32 s9, -1
	v_mul_f32_e32 v177, v32, v175
	v_mul_f32_e32 v176, v47, v177
	v_mul_f32_e32 v47, v46, v176
	v_mul_f32_e32 v46, v45, v47
	v_pk_mul_f32 v[44:45], v[60:61], v[46:47]
	v_mul_f32_e32 v46, v208, v209
	v_mul_f32_e32 v47, v174, v175
	ds_bpermute_b32 v61, v64, v46
	v_pk_mul_f32 v[62:63], v[62:63], v[176:177]
	s_sub_i32 s5, s5, 64
	v_lshl_add_u64 v[170:171], v[170:171], 0, s[8:9]
	s_waitcnt lgkmcnt(0)
	v_cndmask_b32_e64 v32, 1.0, v61, s[42:43]
	v_mul_f32_e32 v175, v32, v47
	v_mul_f32_e32 v174, v43, v175
	v_mul_f32_e32 v43, v42, v174
	v_mul_f32_e32 v42, v41, v43
	v_pk_mul_f32 v[40:41], v[56:57], v[42:43]
	v_mul_f32_e32 v42, v206, v207
	v_mul_f32_e32 v43, v46, v61
	ds_bpermute_b32 v46, v64, v42
	v_pk_mul_f32 v[58:59], v[58:59], v[174:175]
	s_cmp_lg_u32 s4, 0
	s_waitcnt lgkmcnt(0)
	v_cndmask_b32_e64 v32, 1.0, v46, s[42:43]
	v_pk_mul_f32 v[42:43], v[42:43], v[46:47]
	s_nop 0
	v_mul_f32_e32 v47, v32, v43
	v_mul_f32_e32 v46, v39, v47
	v_mul_f32_e32 v39, v38, v46
	v_mul_f32_e32 v38, v37, v39
	v_pk_mul_f32 v[36:37], v[52:53], v[38:39]
	v_mul_f32_e32 v38, v204, v205
	v_mul_f32_e32 v39, v42, v43
	ds_bpermute_b32 v52, v64, v38
	v_pk_mul_f32 v[54:55], v[54:55], v[46:47]
	s_waitcnt lgkmcnt(0)
	v_cndmask_b32_e64 v32, 1.0, v52, s[42:43]
	v_mul_f32_e32 v43, v32, v39
	v_mul_f32_e32 v42, v35, v43
	v_mul_f32_e32 v35, v34, v42
	v_mul_f32_e32 v34, v33, v35
	v_pk_mul_f32 v[46:47], v[50:51], v[42:43]
	v_pk_mul_f32 v[32:33], v[48:49], v[34:35]
	v_mul_f32_e32 v34, v38, v52
	v_mul_f32_e32 v159, v34, v39
	v_cvt_pk_bf16_f32 v32, v32, v33
	v_cvt_pk_bf16_f32 v33, v46, v47
	v_cvt_pk_bf16_f32 v34, v36, v37
	v_cvt_pk_bf16_f32 v35, v54, v55
	s_waitcnt vmcnt(15)
	s_nop 0
	v_mfma_f32_32x32x16_bf16 v[16:31], v[142:145], v[32:35], v[16:31]
	s_waitcnt vmcnt(14)
	v_mfma_f32_32x32x16_bf16 v[0:15], v[138:141], v[32:35], v[0:15]
	v_cvt_pk_bf16_f32 v32, v40, v41
	v_cvt_pk_bf16_f32 v33, v58, v59
	v_cvt_pk_bf16_f32 v34, v44, v45
	v_cvt_pk_bf16_f32 v35, v62, v63
	s_waitcnt vmcnt(13)
	s_nop 0
	v_mfma_f32_32x32x16_bf16 v[16:31], v[134:137], v[32:35], v[16:31]
	s_waitcnt vmcnt(12)
	v_mfma_f32_32x32x16_bf16 v[0:15], v[130:133], v[32:35], v[0:15]
	v_cvt_pk_bf16_f32 v32, v172, v173
	v_cvt_pk_bf16_f32 v33, v178, v179
	v_cvt_pk_bf16_f32 v34, v180, v181
	v_cvt_pk_bf16_f32 v35, v186, v187
	s_waitcnt vmcnt(11)
	s_nop 0
	v_mfma_f32_32x32x16_bf16 v[16:31], v[126:129], v[32:35], v[16:31]
	s_waitcnt vmcnt(10)
	v_mfma_f32_32x32x16_bf16 v[0:15], v[122:125], v[32:35], v[0:15]
	v_cvt_pk_bf16_f32 v32, v188, v189
	v_cvt_pk_bf16_f32 v33, v194, v195
	v_cvt_pk_bf16_f32 v34, v198, v199
	v_cvt_pk_bf16_f32 v35, v196, v197
	s_waitcnt vmcnt(9)
	s_nop 0
	v_mfma_f32_32x32x16_bf16 v[16:31], v[118:121], v[32:35], v[16:31]
	s_waitcnt vmcnt(8)
	v_mfma_f32_32x32x16_bf16 v[0:15], v[114:117], v[32:35], v[0:15]
	s_cbranch_scc0 .LBB0_667
